# attention tile loop hand-rewritten: wave halves ping-pong (MFMA segment vs softmax segment), 3-slot LDS ring, deeper ds_read prefetch, v_max3 tree
# speedup vs baseline: 1.0748x; 1.0748x over previous
; __device__ __forceinline__ int swap23(int p) { return (p & ~12) | ((p & 4) << 1) | ((p & 8) >> 1); }
; #define A_STORE(buf) do { LAS unsigned char* bb = lds + (buf) * ABUF; \
;         *(LAS u32x4*)(bb + kr1 * KT_PITCH + kc1 * 16) = st[0]; *(LAS u32x4*)(bb + kr2 * KT_PITCH + kc2 * 16) = st[1]; *(LAS u32x4*)(bb + kr3 * KT_PITCH + kc3 * 16) = st[2]; \
;         *(LAS u32x4*)(bb + KT_BYTES + vd1 * VT_PITCH + vc * 16) = st[3]; *(LAS u32x4*)(bb + KT_BYTES + vd2 * VT_PITCH + vc * 16) = st[4]; } while (0)
; __device__ __forceinline__ void attn_unit(KParams& P, int l, const AUnit& U, LAS unsigned char* lds) {
;     ...
;     const int kr1 = tid / 20, kc1 = tid % 20, kr2 = (tid + 512) / 20, kc2 = (tid + 512) % 20, kr3 = ((tid & 255) + 1024) / 20, kc3 = ((tid & 255) + 1024) % 20;
;     const int vd1 = tid >> 3, vc = tid & 7, vd2 = vd1 + 64;
;     ...
;     A_LOAD(0); A_STORE(0);
;     __syncthreads();
;     f32x16 o[4];
; #pragma unroll
;     for (int d = 0; d < 4; ++d)
; #pragma unroll
;         for (int r = 0; r < 16; ++r) o[d][r] = 0.f;
;     float mrun = -1e30f, lrun = 0.f;
;     const int koff = swap23(i) * KT_PITCH + 16 * hi, voff = KT_BYTES + i * VT_PITCH + 16 * hi;
;     for (int t = 0; t < U.nt; ++t) {
;         const bool more = t + 1 < U.nt;
;         if (more) A_LOAD(t + 1);
.LBB0_677:
	s_or_b64 exec, exec, s[10:11]
	s_mov_b32 s3, 0x66666667
	v_mul_hi_i32 v1, v0, s3
	v_lshrrev_b32_e32 v2, 31, v1
	v_ashrrev_i32_e32 v1, 3, v1
	v_add_u32_e32 v1, v1, v2
	v_mul_lo_u32 v2, v1, 20
	v_sub_u32_e32 v16, v0, v2
	v_add_u32_e32 v2, 0x200, v0
	v_mul_hi_i32 v3, v2, s3
	v_lshrrev_b32_e32 v4, 31, v3
	v_ashrrev_i32_e32 v3, 3, v3
	v_add_u32_e32 v17, v3, v4
	v_mul_lo_u32 v3, v17, 20
	v_sub_u32_e32 v18, v2, v3
	s_movk_i32 s3, 0x400
	v_mov_b32_e32 v2, 0xff
	v_bitop3_b16 v2, v0, s3, v2 bitop3:0xec
	s_mov_b32 s3, 0xcccd
	v_mul_u32_u24_sdwa v3, v2, s3 dst_sel:DWORD dst_unused:UNUSED_PAD src0_sel:WORD_0 src1_sel:DWORD
	v_lshrrev_b32_e32 v19, 20, v3
	v_mul_lo_u16_e32 v3, 20, v19
	s_movk_i32 s3, 0xa0
	v_sub_u16_e32 v14, v2, v3
	v_mul_lo_u32 v2, v1, s3
	v_ashrrev_i32_e32 v3, 31, v2
	v_lshlrev_b32_e32 v6, 3, v16
	v_mul_lo_u32 v8, v17, s3
	v_lshlrev_b64 v[2:3], 1, v[2:3]
	v_ashrrev_i32_e32 v7, 31, v6
	v_ashrrev_i32_e32 v9, 31, v8
	v_lshlrev_b32_e32 v12, 3, v18
	v_lshl_add_u64 v[4:5], s[0:1], 0, v[2:3]
	v_lshlrev_b64 v[6:7], 1, v[6:7]
	v_lshlrev_b64 v[8:9], 1, v[8:9]
	v_ashrrev_i32_e32 v13, 31, v12
	v_lshl_add_u64 v[4:5], v[4:5], 0, v[6:7]
	v_lshl_add_u64 v[10:11], s[0:1], 0, v[8:9]
	v_lshlrev_b64 v[12:13], 1, v[12:13]
	v_lshl_add_u64 v[10:11], v[10:11], 0, v[12:13]
	global_load_dwordx4 v[136:139], v[4:5], off
	global_load_dwordx4 v[140:143], v[10:11], off
	v_mul_u32_u24_e32 v4, 0xa0, v19
	v_lshlrev_b32_e32 v4, 1, v4
	v_mov_b32_e32 v5, v157
	v_lshl_add_u64 v[10:11], s[0:1], 0, v[4:5]
	v_lshlrev_b32_e32 v166, 4, v14
	v_mov_b32_e32 v167, v157
	v_ashrrev_i32_e32 v20, 3, v0
	v_lshl_add_u64 v[10:11], v[10:11], 0, v[166:167]
	v_add_u32_e32 v21, 64, v20
	global_load_dwordx4 v[144:147], v[10:11], off
	v_mad_i64_i32 v[10:11], s[10:11], s8, v20, 0
	v_lshlrev_b32_e32 v14, 4, v0
	v_lshl_add_u64 v[10:11], v[10:11], 1, s[6:7]
	v_and_b32_e32 v168, 0x70, v14
	v_mov_b32_e32 v169, v157
	v_mad_i64_i32 v[14:15], s[10:11], s8, v21, 0
	v_lshl_add_u64 v[10:11], v[10:11], 0, v[168:169]
	v_lshl_add_u64 v[14:15], v[14:15], 1, s[6:7]
	v_lshl_add_u64 v[14:15], v[14:15], 0, v[168:169]
	global_load_dwordx4 v[148:151], v[10:11], off
	global_load_dwordx4 v[152:155], v[14:15], off
	v_and_b32_e32 v10, 19, v0
	v_lshlrev_b32_e32 v11, 1, v181
	v_lshrrev_b32_e32 v0, 1, v0
	s_add_u32 s6, s6, 0x80
	s_movk_i32 s3, 0x90
	v_mul_lo_u32 v184, v20, s3
	v_and_b32_e32 v11, 8, v11
	v_and_b32_e32 v0, 4, v0
	s_addc_u32 s7, s7, 0
	s_lshl_b32 s3, s8, 1
	s_movk_i32 s8, 0x150
	v_or3_b32 v0, v10, v11, v0
	v_mul_lo_u32 v186, v1, s8
	v_lshlrev_b32_e32 v190, 4, v16
	v_mul_u32_u24_e32 v187, 0x150, v0
	v_mul_lo_u32 v189, v17, s8
	v_add_u32_e32 v0, v186, v190
	v_lshlrev_b32_e32 v191, 4, v18
	v_mad_u32_u24 v1, v19, s8, v166
	v_add_u32_e32 v14, v184, v168
	v_add_u32_e32 v10, v189, v191
	v_mov_b32_e32 v32, v157
	v_mov_b32_e32 v33, v157
	v_mov_b32_e32 v46, v157
	v_mov_b32_e32 v47, v157
	v_mul_u32_u24_e32 v188, 0x150, v19
	v_mov_b32_e32 v34, v157
	v_mov_b32_e32 v35, v157
	v_mov_b32_e32 v36, v157
	v_mov_b32_e32 v37, v157
	v_mov_b32_e32 v38, v157
	v_mov_b32_e32 v39, v157
	v_mov_b32_e32 v40, v157
	v_mov_b32_e32 v41, v157
	v_mov_b32_e32 v42, v157
	v_mov_b32_e32 v43, v157
	v_mov_b32_e32 v44, v157
	v_mov_b32_e32 v45, v157
	v_mov_b64_e32 v[62:63], v[46:47]
	v_ashrrev_i32_e32 v163, 31, v162
	v_lshlrev_b32_e32 v164, 3, v183
	v_mul_u32_u24_e32 v165, 0x90, v181
	v_add_u32_e32 v185, 0x2400, v184
	v_mov_b64_e32 v[60:61], v[44:45]
	v_mov_b64_e32 v[58:59], v[42:43]
	s_waitcnt vmcnt(4)
	ds_write_b128 v0, v[136:139]
	s_waitcnt vmcnt(3)
	ds_write_b128 v10, v[140:143]
	s_waitcnt vmcnt(2)
	ds_write_b128 v1, v[144:147]
	s_waitcnt vmcnt(1)
	ds_write_b128 v14, v[148:151] offset:21504
	s_waitcnt vmcnt(0)
	ds_write_b128 v14, v[152:155] offset:30720
	v_mad_i64_i32 v[0:1], s[8:9], s3, v20, v[168:169]
	v_lshl_add_u64 v[170:171], s[6:7], 0, v[0:1]
	v_mad_i64_i32 v[0:1], s[8:9], s3, v21, v[168:169]
	v_lshl_add_u64 v[172:173], s[6:7], 0, v[0:1]
	v_lshl_add_u64 v[0:1], v[2:3], 0, v[6:7]
	s_mov_b64 s[6:7], 0x5000
	v_lshl_add_u64 v[174:175], v[0:1], 0, s[6:7]
	v_lshl_add_u64 v[0:1], v[8:9], 0, v[12:13]
	v_lshl_add_u64 v[176:177], v[0:1], 0, s[6:7]
	v_lshl_add_u64 v[0:1], v[4:5], 0, v[166:167]
	v_lshl_add_u64 v[178:179], v[0:1], 0, s[6:7]
	v_mov_b64_e32 v[16:17], v[32:33]
	v_mov_b64_e32 v[0:1], v[32:33]
	s_lshl_b32 s3, s89, 6
	s_mov_b32 s6, 0
	v_mov_b32_e32 v169, 0xf149f2ca
	v_mov_b32_e32 v167, 0
	v_mov_b64_e32 v[56:57], v[40:41]
	v_mov_b64_e32 v[54:55], v[38:39]
	v_mov_b64_e32 v[52:53], v[36:37]
	v_mov_b64_e32 v[50:51], v[34:35]
	v_mov_b64_e32 v[48:49], v[32:33]
	v_mov_b64_e32 v[18:19], v[34:35]
	v_mov_b64_e32 v[20:21], v[36:37]
	v_mov_b64_e32 v[22:23], v[38:39]
	v_mov_b64_e32 v[24:25], v[40:41]
	v_mov_b64_e32 v[26:27], v[42:43]
	v_mov_b64_e32 v[28:29], v[44:45]
	v_mov_b64_e32 v[30:31], v[46:47]
	v_mov_b64_e32 v[2:3], v[34:35]
	v_mov_b64_e32 v[4:5], v[36:37]
	v_mov_b64_e32 v[6:7], v[38:39]
	v_mov_b64_e32 v[8:9], v[40:41]
	v_mov_b64_e32 v[10:11], v[42:43]
	v_mov_b64_e32 v[12:13], v[44:45]
	v_mov_b64_e32 v[14:15], v[46:47]
	s_mov_b32 s7, 0
	v_lshl_add_u64 v[174:175], s[0:1], 0, v[174:175]
	v_lshl_add_u64 v[176:177], s[0:1], 0, v[176:177]
	v_lshl_add_u64 v[178:179], s[0:1], 0, v[178:179]
	s_mov_b64 s[26:27], 0x5000
	v_add_u32_e32 v216, v186, v190
	v_add_u32_e32 v217, v189, v191
	v_add_u32_e32 v218, v188, v166
	v_add_u32_e32 v219, v184, v168
	v_add_u32_e32 v220, v185, v168
	s_mov_b32 s20, 0
	s_mov_b32 s22, 0
	s_mov_b32 s23, 0x9c00
	s_mov_b32 s24, 0x13800
	s_cmp_gt_u32 s89, 1
	s_cbranch_scc0 .Lattn_pro_noload
	global_load_dwordx4 v[136:139], v[174:175], off
	global_load_dwordx4 v[140:143], v[176:177], off
	global_load_dwordx4 v[144:147], v[178:179], off
	global_load_dwordx4 v[148:151], v[170:171], off
	global_load_dwordx4 v[152:155], v[172:173], off
	v_lshl_add_u64 v[174:175], v[174:175], 0, s[26:27]
	v_lshl_add_u64 v[176:177], v[176:177], 0, s[26:27]
	v_lshl_add_u64 v[178:179], v[178:179], 0, s[26:27]
	v_lshl_add_u64 v[170:171], v[170:171], 0, s[82:83]
	v_lshl_add_u64 v[172:173], v[172:173], 0, s[82:83]
; #define LAS __attribute__((address_space(3)))
; __device__ __forceinline__ void attn_unit(KParams& P, int l, const AUnit& U, LAS unsigned char* lds) {
;     ...
;     for (int t = 0; t < U.nt; ++t) {
;         const bool more = t + 1 < U.nt;
;         if (more) A_LOAD(t + 1);
;         const LAS unsigned char* bb = lds + (t & 1) * ABUF;
;         f32x16 p0, p1;
; #pragma unroll
;         for (int r = 0; r < 16; ++r) { p0[r] = 0.f; p1[r] = 0.f; }
; #pragma unroll
;         for (int s = 0; s < 10; ++s) {
;             const bf16x8 k0 = *(const LAS bf16x8*)(bb + koff + 32 * s), k1 = *(const LAS bf16x8*)(bb + koff + 32 * KT_PITCH + 32 * s);
;             p0 = __builtin_amdgcn_mfma_f32_32x32x16_bf16(k0, qf[s], p0, 0, 0, 0);
;             p1 = __builtin_amdgcn_mfma_f32_32x32x16_bf16(k1, qf[s], p1, 0, 0, 0);
;         }
;         if ((t + 1) * 64 > U.kvlen) {
;             const int kb0 = t * 64 + 8 * hi;
; #pragma unroll
;             for (int r = 0; r < 16; ++r) { const int kv = kb0 + 16 * (r >> 3) + (r & 7); if (kv >= U.kvlen) p0[r] = -INFINITY; if (kv + 32 >= U.kvlen) p1[r] = -INFINITY; }
.Lattn_pro_noload:
	s_waitcnt lgkmcnt(0)
	s_barrier
	s_cmp_lt_u32 s88, 4
	s_cbranch_scc1 .Lattn_x0
	s_barrier
.Lattn_x0:
	s_mov_b32 s23, 0
	s_mov_b32 s24, 0x9c00
	v_add3_u32 v230, s23, v187, v156
	ds_read_b128 v[192:195], v230
	ds_read_b128 v[196:199], v230 offset:10752
	ds_read_b128 v[200:203], v230 offset:32
	ds_read_b128 v[204:207], v230 offset:10784
	ds_read_b128 v[208:211], v230 offset:64
	ds_read_b128 v[226:229], v230 offset:10816
	ds_read_b128 v[234:237], v230 offset:96
	s_waitcnt lgkmcnt(6)
	v_mfma_f32_32x32x16_bf16 v[80:95], v[192:195], v[96:99], 0
	ds_read_b128 v[238:241], v230 offset:10848
	s_waitcnt lgkmcnt(6)
	v_mfma_f32_32x32x16_bf16 v[64:79], v[196:199], v[96:99], 0
	ds_read_b128 v[192:195], v230 offset:128
	s_waitcnt lgkmcnt(6)
	v_mfma_f32_32x32x16_bf16 v[80:95], v[200:203], v[100:103], v[80:95]
	ds_read_b128 v[196:199], v230 offset:10880
	s_waitcnt lgkmcnt(6)
	v_mfma_f32_32x32x16_bf16 v[64:79], v[204:207], v[100:103], v[64:79]
	ds_read_b128 v[200:203], v230 offset:160
	s_waitcnt lgkmcnt(6)
	v_mfma_f32_32x32x16_bf16 v[80:95], v[208:211], v[104:107], v[80:95]
	ds_read_b128 v[204:207], v230 offset:10912
	s_waitcnt lgkmcnt(6)
	v_mfma_f32_32x32x16_bf16 v[64:79], v[226:229], v[104:107], v[64:79]
	ds_read_b128 v[208:211], v230 offset:192
	s_waitcnt lgkmcnt(6)
	v_mfma_f32_32x32x16_bf16 v[80:95], v[234:237], v[108:111], v[80:95]
	ds_read_b128 v[226:229], v230 offset:10944
	s_waitcnt vmcnt(0)
	v_add_u32_e32 v221, s24, v216
	ds_write_b128 v221, v[136:139]
	v_add_u32_e32 v221, s24, v217
	ds_write_b128 v221, v[140:143]
	v_add_u32_e32 v221, s24, v218
	ds_write_b128 v221, v[144:147]
	v_add_u32_e32 v221, s24, v219
	ds_write_b128 v221, v[148:151] offset:21504
	v_add_u32_e32 v221, s24, v220
	ds_write_b128 v221, v[152:155] offset:21504
	s_waitcnt lgkmcnt(11)
	v_mfma_f32_32x32x16_bf16 v[64:79], v[238:241], v[108:111], v[64:79]
	ds_read_b128 v[234:237], v230 offset:224
	s_waitcnt lgkmcnt(11)
	v_mfma_f32_32x32x16_bf16 v[80:95], v[192:195], v[112:115], v[80:95]
	ds_read_b128 v[238:241], v230 offset:10976
	s_waitcnt lgkmcnt(11)
	v_mfma_f32_32x32x16_bf16 v[64:79], v[196:199], v[112:115], v[64:79]
	ds_read_b128 v[192:195], v230 offset:256
	s_waitcnt lgkmcnt(11)
	v_mfma_f32_32x32x16_bf16 v[80:95], v[200:203], v[116:119], v[80:95]
	ds_read_b128 v[196:199], v230 offset:11008
	s_add_i32 s25, s20, 2
	s_cmp_lt_u32 s25, s89
	s_cbranch_scc0 .Lattn_noload_x0
	global_load_dwordx4 v[136:139], v[174:175], off
	global_load_dwordx4 v[140:143], v[176:177], off
	global_load_dwordx4 v[144:147], v[178:179], off
	global_load_dwordx4 v[148:151], v[170:171], off
	global_load_dwordx4 v[152:155], v[172:173], off
	v_lshl_add_u64 v[174:175], v[174:175], 0, s[26:27]
	v_lshl_add_u64 v[176:177], v[176:177], 0, s[26:27]
	v_lshl_add_u64 v[178:179], v[178:179], 0, s[26:27]
	v_lshl_add_u64 v[170:171], v[170:171], 0, s[82:83]
	v_lshl_add_u64 v[172:173], v[172:173], 0, s[82:83]
.Lattn_noload_x0:
	s_waitcnt lgkmcnt(11)
	v_mfma_f32_32x32x16_bf16 v[64:79], v[204:207], v[116:119], v[64:79]
	ds_read_b128 v[200:203], v230 offset:288
	s_waitcnt lgkmcnt(11)
	v_mfma_f32_32x32x16_bf16 v[80:95], v[208:211], v[120:123], v[80:95]
	ds_read_b128 v[204:207], v230 offset:11040
	s_waitcnt lgkmcnt(11)
	v_mfma_f32_32x32x16_bf16 v[64:79], v[226:229], v[120:123], v[64:79]
	s_waitcnt lgkmcnt(5)
	v_mfma_f32_32x32x16_bf16 v[80:95], v[234:237], v[124:127], v[80:95]
	s_waitcnt lgkmcnt(4)
	v_mfma_f32_32x32x16_bf16 v[64:79], v[238:241], v[124:127], v[64:79]
	s_waitcnt lgkmcnt(3)
	v_mfma_f32_32x32x16_bf16 v[80:95], v[192:195], v[128:131], v[80:95]
	s_waitcnt lgkmcnt(2)
	v_mfma_f32_32x32x16_bf16 v[64:79], v[196:199], v[128:131], v[64:79]
	s_waitcnt lgkmcnt(1)
	v_mfma_f32_32x32x16_bf16 v[80:95], v[200:203], v[132:135], v[80:95]
	s_waitcnt lgkmcnt(0)
	v_mfma_f32_32x32x16_bf16 v[64:79], v[204:207], v[132:135], v[64:79]
	s_waitcnt lgkmcnt(0)
	s_mov_b32 s22, 0
	s_mov_b32 s23, 0x9c00
	s_mov_b32 s24, 0x13800
.Lattn_loop:
	s_barrier
	s_nop 15
	s_nop 3
	s_lshl_b32 s25, s20, 6
	s_add_i32 s28, s25, 64
	s_cmp_le_u32 s28, s70
	s_cbranch_scc1 .Lattn_nomask
	v_add_u32_e32 v208, s25, v164
	v_add_u32_e32 v209, 0, v208
	v_cmp_gt_u32_e32 vcc, s70, v209
	v_cndmask_b32_e32 v80, v225, v80, vcc
	v_add_u32_e32 v209, 32, v208
	v_cmp_gt_u32_e32 vcc, s70, v209
	v_cndmask_b32_e32 v64, v225, v64, vcc
	v_add_u32_e32 v209, 1, v208
	v_cmp_gt_u32_e32 vcc, s70, v209
	v_cndmask_b32_e32 v81, v225, v81, vcc
	v_add_u32_e32 v209, 33, v208
	v_cmp_gt_u32_e32 vcc, s70, v209
	v_cndmask_b32_e32 v65, v225, v65, vcc
	v_add_u32_e32 v209, 2, v208
	v_cmp_gt_u32_e32 vcc, s70, v209
	v_cndmask_b32_e32 v82, v225, v82, vcc
	v_add_u32_e32 v209, 34, v208
	v_cmp_gt_u32_e32 vcc, s70, v209
	v_cndmask_b32_e32 v66, v225, v66, vcc
	v_add_u32_e32 v209, 3, v208
	v_cmp_gt_u32_e32 vcc, s70, v209
	v_cndmask_b32_e32 v83, v225, v83, vcc
	v_add_u32_e32 v209, 35, v208
	v_cmp_gt_u32_e32 vcc, s70, v209
	v_cndmask_b32_e32 v67, v225, v67, vcc
	v_add_u32_e32 v209, 4, v208
	v_cmp_gt_u32_e32 vcc, s70, v209
	v_cndmask_b32_e32 v84, v225, v84, vcc
	v_add_u32_e32 v209, 36, v208
	v_cmp_gt_u32_e32 vcc, s70, v209
	v_cndmask_b32_e32 v68, v225, v68, vcc
	v_add_u32_e32 v209, 5, v208
	v_cmp_gt_u32_e32 vcc, s70, v209
	v_cndmask_b32_e32 v85, v225, v85, vcc
	v_add_u32_e32 v209, 37, v208
	v_cmp_gt_u32_e32 vcc, s70, v209
	v_cndmask_b32_e32 v69, v225, v69, vcc
	v_add_u32_e32 v209, 6, v208
	v_cmp_gt_u32_e32 vcc, s70, v209
	v_cndmask_b32_e32 v86, v225, v86, vcc
	v_add_u32_e32 v209, 38, v208
	v_cmp_gt_u32_e32 vcc, s70, v209
	v_cndmask_b32_e32 v70, v225, v70, vcc
	v_add_u32_e32 v209, 7, v208
	v_cmp_gt_u32_e32 vcc, s70, v209
	v_cndmask_b32_e32 v87, v225, v87, vcc
	v_add_u32_e32 v209, 39, v208
; __device__ __forceinline__ void attn_unit(KParams& P, int l, const AUnit& U, LAS unsigned char* lds) {
;     ...
;             for (int r = 0; r < 16; ++r) { const int kv = kb0 + 16 * (r >> 3) + (r & 7); if (kv >= U.kvlen) p0[r] = -INFINITY; if (kv + 32 >= U.kvlen) p1[r] = -INFINITY; }
;         }
;         float mx = fmaxf(p0[0], p1[0]);
; #pragma unroll
;         for (int r = 1; r < 16; ++r) mx = fmaxf(mx, fmaxf(p0[r], p1[r]));
;         { const auto rr = __builtin_amdgcn_permlane32_swap(__float_as_uint(mx), __float_as_uint(mx), false, false);
;           mx = fmaxf(__uint_as_float(rr[0]), __uint_as_float(rr[1])); }
;         const float mnew = fmaxf(mrun, mx); const float f = __builtin_amdgcn_exp2f(mrun - mnew); const bool grew = __any(mnew > mrun); mrun = mnew;
;         f32x2 ps2 = {0.f, 0.f}; const f32x2 nm2 = {-mnew, -mnew};
; #pragma unroll
;         for (int r = 0; r < 16; r += 2) { f32x2 a = (f32x2){p0[r], p0[r + 1]} + nm2, b = (f32x2){p1[r], p1[r + 1]} + nm2;
;             a[0] = __builtin_amdgcn_exp2f(a[0]); a[1] = __builtin_amdgcn_exp2f(a[1]); b[0] = __builtin_amdgcn_exp2f(b[0]); b[1] = __builtin_amdgcn_exp2f(b[1]);
;             p0[r] = a[0]; p0[r + 1] = a[1]; p1[r] = b[0]; p1[r + 1] = b[1]; ps2 += a; ps2 += b; }
;         const float ps = ps2[0] + ps2[1];
;         lrun = lrun * f + ps;
;         if (grew) {
; #pragma unroll
;             for (int d = 0; d < 4; ++d)
; #pragma unroll
;                 for (int r = 0; r < 16; ++r) o[d][r] *= f;
;         }
	v_cmp_gt_u32_e32 vcc, s70, v209
	v_cndmask_b32_e32 v71, v225, v71, vcc
	v_add_u32_e32 v209, 16, v208
	v_cmp_gt_u32_e32 vcc, s70, v209
	v_cndmask_b32_e32 v88, v225, v88, vcc
	v_add_u32_e32 v209, 48, v208
	v_cmp_gt_u32_e32 vcc, s70, v209
	v_cndmask_b32_e32 v72, v225, v72, vcc
	v_add_u32_e32 v209, 17, v208
	v_cmp_gt_u32_e32 vcc, s70, v209
	v_cndmask_b32_e32 v89, v225, v89, vcc
	v_add_u32_e32 v209, 49, v208
	v_cmp_gt_u32_e32 vcc, s70, v209
	v_cndmask_b32_e32 v73, v225, v73, vcc
	v_add_u32_e32 v209, 18, v208
	v_cmp_gt_u32_e32 vcc, s70, v209
	v_cndmask_b32_e32 v90, v225, v90, vcc
	v_add_u32_e32 v209, 50, v208
	v_cmp_gt_u32_e32 vcc, s70, v209
	v_cndmask_b32_e32 v74, v225, v74, vcc
	v_add_u32_e32 v209, 19, v208
	v_cmp_gt_u32_e32 vcc, s70, v209
	v_cndmask_b32_e32 v91, v225, v91, vcc
	v_add_u32_e32 v209, 51, v208
	v_cmp_gt_u32_e32 vcc, s70, v209
	v_cndmask_b32_e32 v75, v225, v75, vcc
	v_add_u32_e32 v209, 20, v208
	v_cmp_gt_u32_e32 vcc, s70, v209
	v_cndmask_b32_e32 v92, v225, v92, vcc
	v_add_u32_e32 v209, 52, v208
	v_cmp_gt_u32_e32 vcc, s70, v209
	v_cndmask_b32_e32 v76, v225, v76, vcc
	v_add_u32_e32 v209, 21, v208
	v_cmp_gt_u32_e32 vcc, s70, v209
	v_cndmask_b32_e32 v93, v225, v93, vcc
	v_add_u32_e32 v209, 53, v208
	v_cmp_gt_u32_e32 vcc, s70, v209
	v_cndmask_b32_e32 v77, v225, v77, vcc
	v_add_u32_e32 v209, 22, v208
	v_cmp_gt_u32_e32 vcc, s70, v209
	v_cndmask_b32_e32 v94, v225, v94, vcc
	v_add_u32_e32 v209, 54, v208
	v_cmp_gt_u32_e32 vcc, s70, v209
	v_cndmask_b32_e32 v78, v225, v78, vcc
	v_add_u32_e32 v209, 23, v208
	v_cmp_gt_u32_e32 vcc, s70, v209
	v_cndmask_b32_e32 v95, v225, v95, vcc
	v_add_u32_e32 v209, 55, v208
	v_cmp_gt_u32_e32 vcc, s70, v209
	v_cndmask_b32_e32 v79, v225, v79, vcc
.Lattn_nomask:
	v_max3_f32 v208, v80, v81, v82
	v_max3_f32 v209, v83, v84, v85
	v_max3_f32 v210, v86, v87, v88
	v_max3_f32 v211, v89, v90, v91
	v_max3_f32 v208, v208, v92, v93
	v_max3_f32 v209, v209, v94, v95
	v_max3_f32 v210, v210, v64, v65
	v_max3_f32 v211, v211, v66, v67
	v_max3_f32 v208, v208, v68, v69
	v_max3_f32 v209, v209, v70, v71
	v_max3_f32 v210, v210, v72, v73
	v_max3_f32 v211, v211, v74, v75
	v_max3_f32 v208, v208, v76, v77
	v_max3_f32 v209, v209, v78, v79
	v_max3_f32 v208, v208, v209, v210
	v_max_f32_e32 v208, v208, v211
	v_mov_b32_e32 v209, v208
	s_nop 1
	v_permlane32_swap_b32_e32 v208, v209
	v_max3_f32 v180, v169, v208, v209
	v_sub_f32_e32 v182, v169, v180
	v_exp_f32_e32 v182, v182
	v_cmp_gt_f32_e32 vcc, v180, v169
	s_cbranch_vccz .Lattn_norescale
	v_pk_mul_f32 v[62:63], v[62:63], v[182:183] op_sel_hi:[1,0]
	v_pk_mul_f32 v[60:61], v[60:61], v[182:183] op_sel_hi:[1,0]
	v_pk_mul_f32 v[58:59], v[58:59], v[182:183] op_sel_hi:[1,0]
	v_pk_mul_f32 v[56:57], v[56:57], v[182:183] op_sel_hi:[1,0]
	v_pk_mul_f32 v[54:55], v[54:55], v[182:183] op_sel_hi:[1,0]
	v_pk_mul_f32 v[52:53], v[52:53], v[182:183] op_sel_hi:[1,0]
	v_pk_mul_f32 v[50:51], v[50:51], v[182:183] op_sel_hi:[1,0]
	v_pk_mul_f32 v[48:49], v[48:49], v[182:183] op_sel_hi:[1,0]
	v_pk_mul_f32 v[46:47], v[46:47], v[182:183] op_sel_hi:[1,0]
	v_pk_mul_f32 v[44:45], v[44:45], v[182:183] op_sel_hi:[1,0]
	v_pk_mul_f32 v[42:43], v[42:43], v[182:183] op_sel_hi:[1,0]
	v_pk_mul_f32 v[40:41], v[40:41], v[182:183] op_sel_hi:[1,0]
	v_pk_mul_f32 v[38:39], v[38:39], v[182:183] op_sel_hi:[1,0]
	v_pk_mul_f32 v[36:37], v[36:37], v[182:183] op_sel_hi:[1,0]
	v_pk_mul_f32 v[34:35], v[34:35], v[182:183] op_sel_hi:[1,0]
	v_pk_mul_f32 v[32:33], v[32:33], v[182:183] op_sel_hi:[1,0]
	v_pk_mul_f32 v[30:31], v[30:31], v[182:183] op_sel_hi:[1,0]
	v_pk_mul_f32 v[28:29], v[28:29], v[182:183] op_sel_hi:[1,0]
	v_pk_mul_f32 v[26:27], v[26:27], v[182:183] op_sel_hi:[1,0]
	v_pk_mul_f32 v[24:25], v[24:25], v[182:183] op_sel_hi:[1,0]
	v_pk_mul_f32 v[22:23], v[22:23], v[182:183] op_sel_hi:[1,0]
	v_pk_mul_f32 v[20:21], v[20:21], v[182:183] op_sel_hi:[1,0]
	v_pk_mul_f32 v[18:19], v[18:19], v[182:183] op_sel_hi:[1,0]
	v_pk_mul_f32 v[16:17], v[16:17], v[182:183] op_sel_hi:[1,0]
	v_pk_mul_f32 v[14:15], v[14:15], v[182:183] op_sel_hi:[1,0]
	v_pk_mul_f32 v[12:13], v[12:13], v[182:183] op_sel_hi:[1,0]
	v_pk_mul_f32 v[10:11], v[10:11], v[182:183] op_sel_hi:[1,0]
	v_pk_mul_f32 v[8:9], v[8:9], v[182:183] op_sel_hi:[1,0]
	v_pk_mul_f32 v[6:7], v[6:7], v[182:183] op_sel_hi:[1,0]
	v_pk_mul_f32 v[4:5], v[4:5], v[182:183] op_sel_hi:[1,0]
	v_pk_mul_f32 v[2:3], v[2:3], v[182:183] op_sel_hi:[1,0]
	v_pk_mul_f32 v[0:1], v[0:1], v[182:183] op_sel_hi:[1,0]
; #define LAS __attribute__((address_space(3)))
; __device__ __forceinline__ unsigned cvt_pk_bf16(float lo, float hi) { f32x2 v = {lo, hi}; bf16x2_t b = __builtin_convertvector(v, bf16x2_t); return __builtin_bit_cast(unsigned, b); }
; __device__ __forceinline__ void attn_unit(KParams& P, int l, const AUnit& U, LAS unsigned char* lds) {
;     ...
;         const float mnew = fmaxf(mrun, mx); const float f = __builtin_amdgcn_exp2f(mrun - mnew); const bool grew = __any(mnew > mrun); mrun = mnew;
;         f32x2 ps2 = {0.f, 0.f}; const f32x2 nm2 = {-mnew, -mnew};
; #pragma unroll
;         for (int r = 0; r < 16; r += 2) { f32x2 a = (f32x2){p0[r], p0[r + 1]} + nm2, b = (f32x2){p1[r], p1[r + 1]} + nm2;
;             a[0] = __builtin_amdgcn_exp2f(a[0]); a[1] = __builtin_amdgcn_exp2f(a[1]); b[0] = __builtin_amdgcn_exp2f(b[0]); b[1] = __builtin_amdgcn_exp2f(b[1]);
;             p0[r] = a[0]; p0[r + 1] = a[1]; p1[r] = b[0]; p1[r + 1] = b[1]; ps2 += a; ps2 += b; }
;         const float ps = ps2[0] + ps2[1];
;         lrun = lrun * f + ps;
;         if (grew) {
; #pragma unroll
;             for (int d = 0; d < 4; ++d)
; #pragma unroll
;                 for (int r = 0; r < 16; ++r) o[d][r] *= f;
;         }
;         bf16x8 pf[4];
;         { u32x4 w;
;           w.x = cvt_pk_bf16(p0[0], p0[1]); w.y = cvt_pk_bf16(p0[2], p0[3]); w.z = cvt_pk_bf16(p0[4], p0[5]); w.w = cvt_pk_bf16(p0[6], p0[7]); pf[0] = __builtin_bit_cast(bf16x8, w);
;           w.x = cvt_pk_bf16(p0[8], p0[9]); w.y = cvt_pk_bf16(p0[10], p0[11]); w.z = cvt_pk_bf16(p0[12], p0[13]); w.w = cvt_pk_bf16(p0[14], p0[15]); pf[1] = __builtin_bit_cast(bf16x8, w);
;           w.x = cvt_pk_bf16(p1[0], p1[1]); w.y = cvt_pk_bf16(p1[2], p1[3]); w.z = cvt_pk_bf16(p1[4], p1[5]); w.w = cvt_pk_bf16(p1[6], p1[7]); pf[2] = __builtin_bit_cast(bf16x8, w);
;           w.x = cvt_pk_bf16(p1[8], p1[9]); w.y = cvt_pk_bf16(p1[10], p1[11]); w.z = cvt_pk_bf16(p1[12], p1[13]); w.w = cvt_pk_bf16(p1[14], p1[15]); pf[3] = __builtin_bit_cast(bf16x8, w); }
; #pragma unroll
;         for (int d = 0; d < 4; ++d)
; #pragma unroll
;             for (int ks = 0; ks < 4; ++ks) {
;                 const bf16x8 vf = *(const LAS bf16x8*)(bb + voff + d * 32 * VT_PITCH + 32 * ks);
;                 o[d] = __builtin_amdgcn_mfma_f32_32x32x16_bf16(vf, pf[ks], o[d], 0, 0, 0);
;             }
;         if (more) A_STORE((t + 1) & 1);
.Lattn_norescale:
	v_mov_b32_e32 v169, v180
	v_sub_f32_e32 v80, v80, v180
	v_sub_f32_e32 v81, v81, v180
	v_sub_f32_e32 v82, v82, v180
	v_sub_f32_e32 v83, v83, v180
	v_sub_f32_e32 v84, v84, v180
	v_sub_f32_e32 v85, v85, v180
	v_sub_f32_e32 v86, v86, v180
	v_sub_f32_e32 v87, v87, v180
	v_sub_f32_e32 v88, v88, v180
	v_sub_f32_e32 v89, v89, v180
	v_sub_f32_e32 v90, v90, v180
	v_sub_f32_e32 v91, v91, v180
	v_sub_f32_e32 v92, v92, v180
	v_sub_f32_e32 v93, v93, v180
	v_sub_f32_e32 v94, v94, v180
	v_sub_f32_e32 v95, v95, v180
	v_exp_f32_e32 v80, v80
	v_exp_f32_e32 v81, v81
	v_exp_f32_e32 v82, v82
	v_exp_f32_e32 v83, v83
	v_exp_f32_e32 v84, v84
	v_exp_f32_e32 v85, v85
	v_exp_f32_e32 v86, v86
	v_exp_f32_e32 v87, v87
	v_sub_f32_e32 v64, v64, v180
	v_sub_f32_e32 v65, v65, v180
	v_sub_f32_e32 v66, v66, v180
	v_sub_f32_e32 v67, v67, v180
	v_sub_f32_e32 v68, v68, v180
	v_sub_f32_e32 v69, v69, v180
	v_sub_f32_e32 v70, v70, v180
	v_sub_f32_e32 v71, v71, v180
	v_exp_f32_e32 v88, v88
	v_exp_f32_e32 v89, v89
	v_exp_f32_e32 v90, v90
	v_exp_f32_e32 v91, v91
	v_exp_f32_e32 v92, v92
	v_exp_f32_e32 v93, v93
	v_exp_f32_e32 v94, v94
	v_exp_f32_e32 v95, v95
	v_add_f32_e32 v208, v80, v81
	v_add_f32_e32 v208, v208, v82
	v_add_f32_e32 v208, v208, v83
	v_add_f32_e32 v208, v208, v84
	v_add_f32_e32 v208, v208, v85
	v_add_f32_e32 v208, v208, v86
	v_add_f32_e32 v208, v208, v87
	v_sub_f32_e32 v72, v72, v180
	v_sub_f32_e32 v73, v73, v180
	v_sub_f32_e32 v74, v74, v180
	v_sub_f32_e32 v75, v75, v180
	v_sub_f32_e32 v76, v76, v180
	v_sub_f32_e32 v77, v77, v180
	v_sub_f32_e32 v78, v78, v180
	v_sub_f32_e32 v79, v79, v180
	v_exp_f32_e32 v64, v64
	v_exp_f32_e32 v65, v65
	v_exp_f32_e32 v66, v66
	v_exp_f32_e32 v67, v67
	v_exp_f32_e32 v68, v68
	v_exp_f32_e32 v69, v69
	v_exp_f32_e32 v70, v70
	v_exp_f32_e32 v71, v71
	v_add_f32_e32 v209, v88, v89
	v_add_f32_e32 v209, v209, v90
	v_add_f32_e32 v209, v209, v91
	v_add_f32_e32 v209, v209, v92
	v_add_f32_e32 v209, v209, v93
	v_add_f32_e32 v209, v209, v94
	v_add_f32_e32 v209, v209, v95
	v_cvt_pk_bf16_f32 v80, v80, v81
	v_cvt_pk_bf16_f32 v81, v82, v83
	v_cvt_pk_bf16_f32 v82, v84, v85
	v_cvt_pk_bf16_f32 v83, v86, v87
	v_exp_f32_e32 v72, v72
	v_exp_f32_e32 v73, v73
	v_exp_f32_e32 v74, v74
	v_exp_f32_e32 v75, v75
	v_exp_f32_e32 v76, v76
	v_exp_f32_e32 v77, v77
	v_exp_f32_e32 v78, v78
	v_exp_f32_e32 v79, v79
	v_add_f32_e32 v210, v64, v65
	v_add_f32_e32 v210, v210, v66
	v_add_f32_e32 v210, v210, v67
	v_add_f32_e32 v210, v210, v68
	v_add_f32_e32 v210, v210, v69
	v_add_f32_e32 v210, v210, v70
	v_add_f32_e32 v210, v210, v71
	v_cvt_pk_bf16_f32 v84, v88, v89
	v_cvt_pk_bf16_f32 v85, v90, v91
	v_cvt_pk_bf16_f32 v86, v92, v93
	v_cvt_pk_bf16_f32 v87, v94, v95
	v_add_f32_e32 v211, v72, v73
	v_add_f32_e32 v211, v211, v74
	v_add_f32_e32 v211, v211, v75
	v_add_f32_e32 v211, v211, v76
	v_add_f32_e32 v211, v211, v77
	v_add_f32_e32 v211, v211, v78
	v_add_f32_e32 v211, v211, v79
	v_cvt_pk_bf16_f32 v64, v64, v65
	v_cvt_pk_bf16_f32 v65, v66, v67
	v_cvt_pk_bf16_f32 v66, v68, v69
	v_cvt_pk_bf16_f32 v67, v70, v71
	v_cvt_pk_bf16_f32 v68, v72, v73
	v_cvt_pk_bf16_f32 v69, v74, v75
	v_cvt_pk_bf16_f32 v70, v76, v77
	v_cvt_pk_bf16_f32 v71, v78, v79
	v_add_f32_e32 v208, v208, v209
	v_add_f32_e32 v210, v210, v211
	v_add_f32_e32 v208, v208, v210
	v_fmac_f32_e32 v208, v167, v182
	v_mov_b32_e32 v167, v208
	v_add3_u32 v231, s22, v165, v156
	ds_read_b128 v[192:195], v231 offset:21504
	ds_read_b128 v[196:199], v231 offset:21536
	ds_read_b128 v[200:203], v231 offset:21568
	ds_read_b128 v[204:207], v231 offset:21600
	ds_read_b128 v[208:211], v231 offset:26112
	ds_read_b128 v[226:229], v231 offset:26144
	ds_read_b128 v[234:237], v231 offset:26176
	s_barrier
	s_add_i32 s25, s20, 1
	s_cmp_lt_u32 s25, s89
	s_cbranch_scc0 .Lattn_xlast
	v_add3_u32 v230, s23, v187, v156
	s_waitcnt lgkmcnt(6)
	v_mfma_f32_32x32x16_bf16 v[48:63], v[192:195], v[80:83], v[48:63]
	ds_read_b128 v[238:241], v231 offset:26208
	s_waitcnt lgkmcnt(6)
	v_mfma_f32_32x32x16_bf16 v[48:63], v[196:199], v[84:87], v[48:63]
	ds_read_b128 v[192:195], v231 offset:30720
	s_waitcnt lgkmcnt(6)
	v_mfma_f32_32x32x16_bf16 v[48:63], v[200:203], v[64:67], v[48:63]
	ds_read_b128 v[196:199], v231 offset:30752
	s_waitcnt lgkmcnt(6)
	v_mfma_f32_32x32x16_bf16 v[48:63], v[204:207], v[68:71], v[48:63]
	ds_read_b128 v[200:203], v231 offset:30784
	s_waitcnt lgkmcnt(6)
	v_mfma_f32_32x32x16_bf16 v[32:47], v[208:211], v[80:83], v[32:47]
	ds_read_b128 v[204:207], v231 offset:30816
	s_waitcnt lgkmcnt(6)
	v_mfma_f32_32x32x16_bf16 v[32:47], v[226:229], v[84:87], v[32:47]
	ds_read_b128 v[208:211], v231 offset:35328
	s_waitcnt lgkmcnt(6)
	v_mfma_f32_32x32x16_bf16 v[32:47], v[234:237], v[64:67], v[32:47]
	ds_read_b128 v[226:229], v231 offset:35360
	s_waitcnt lgkmcnt(6)
	v_mfma_f32_32x32x16_bf16 v[32:47], v[238:241], v[68:71], v[32:47]
	ds_read_b128 v[234:237], v231 offset:35392
	s_waitcnt lgkmcnt(6)
	v_mfma_f32_32x32x16_bf16 v[16:31], v[192:195], v[80:83], v[16:31]
	ds_read_b128 v[238:241], v231 offset:35424
	s_waitcnt lgkmcnt(6)
	v_mfma_f32_32x32x16_bf16 v[16:31], v[196:199], v[84:87], v[16:31]
	ds_read_b128 v[192:195], v230
	s_waitcnt lgkmcnt(6)
	v_mfma_f32_32x32x16_bf16 v[16:31], v[200:203], v[64:67], v[16:31]
	ds_read_b128 v[196:199], v230 offset:10752
	s_waitcnt vmcnt(0)
	v_add_u32_e32 v221, s24, v216
	ds_write_b128 v221, v[136:139]
	v_add_u32_e32 v221, s24, v217
	ds_write_b128 v221, v[140:143]
	v_add_u32_e32 v221, s24, v218
	ds_write_b128 v221, v[144:147]
	v_add_u32_e32 v221, s24, v219
	ds_write_b128 v221, v[148:151] offset:21504
	v_add_u32_e32 v221, s24, v220
	ds_write_b128 v221, v[152:155] offset:21504
	s_waitcnt lgkmcnt(11)
	v_mfma_f32_32x32x16_bf16 v[16:31], v[204:207], v[68:71], v[16:31]
	ds_read_b128 v[200:203], v230 offset:32
	s_waitcnt lgkmcnt(11)
	v_mfma_f32_32x32x16_bf16 v[0:15], v[208:211], v[80:83], v[0:15]
	ds_read_b128 v[204:207], v230 offset:10784
	s_waitcnt lgkmcnt(11)
	v_mfma_f32_32x32x16_bf16 v[0:15], v[226:229], v[84:87], v[0:15]
	ds_read_b128 v[208:211], v230 offset:64
	s_waitcnt lgkmcnt(11)
	v_mfma_f32_32x32x16_bf16 v[0:15], v[234:237], v[64:67], v[0:15]
	ds_read_b128 v[226:229], v230 offset:10816
	s_add_i32 s25, s20, 3
	s_cmp_lt_u32 s25, s89
	s_cbranch_scc0 .Lattn_noload_xf
	global_load_dwordx4 v[136:139], v[174:175], off
	global_load_dwordx4 v[140:143], v[176:177], off
	global_load_dwordx4 v[144:147], v[178:179], off
	global_load_dwordx4 v[148:151], v[170:171], off
	global_load_dwordx4 v[152:155], v[172:173], off
	v_lshl_add_u64 v[174:175], v[174:175], 0, s[26:27]
	v_lshl_add_u64 v[176:177], v[176:177], 0, s[26:27]
	v_lshl_add_u64 v[178:179], v[178:179], 0, s[26:27]
	v_lshl_add_u64 v[170:171], v[170:171], 0, s[82:83]
	v_lshl_add_u64 v[172:173], v[172:173], 0, s[82:83]
; #define LAS __attribute__((address_space(3)))
; #define A_STORE(buf) do { LAS unsigned char* bb = lds + (buf) * ABUF; \
;         *(LAS u32x4*)(bb + kr1 * KT_PITCH + kc1 * 16) = st[0]; *(LAS u32x4*)(bb + kr2 * KT_PITCH + kc2 * 16) = st[1]; *(LAS u32x4*)(bb + kr3 * KT_PITCH + kc3 * 16) = st[2]; \
;         *(LAS u32x4*)(bb + KT_BYTES + vd1 * VT_PITCH + vc * 16) = st[3]; *(LAS u32x4*)(bb + KT_BYTES + vd2 * VT_PITCH + vc * 16) = st[4]; } while (0)
; __device__ __forceinline__ void attn_unit(KParams& P, int l, const AUnit& U, LAS unsigned char* lds) {
;     ...
;         for (int s = 0; s < 10; ++s) {
;             const bf16x8 k0 = *(const LAS bf16x8*)(bb + koff + 32 * s), k1 = *(const LAS bf16x8*)(bb + koff + 32 * KT_PITCH + 32 * s);
;             p0 = __builtin_amdgcn_mfma_f32_32x32x16_bf16(k0, qf[s], p0, 0, 0, 0);
;             p1 = __builtin_amdgcn_mfma_f32_32x32x16_bf16(k1, qf[s], p1, 0, 0, 0);
;         }
;     ...
;         for (int d = 0; d < 4; ++d)
; #pragma unroll
;             for (int ks = 0; ks < 4; ++ks) {
;                 const bf16x8 vf = *(const LAS bf16x8*)(bb + voff + d * 32 * VT_PITCH + 32 * ks);
;                 o[d] = __builtin_amdgcn_mfma_f32_32x32x16_bf16(vf, pf[ks], o[d], 0, 0, 0);
;             }
;         if (more) A_STORE((t + 1) & 1);
;         __syncthreads();
;     }
;     ...
;     const float ltot = lrun + __shfl_xor(lrun, 32); const float linv = __builtin_amdgcn_rcpf(ltot);
.Lattn_noload_xf:
	s_waitcnt lgkmcnt(11)
	v_mfma_f32_32x32x16_bf16 v[0:15], v[238:241], v[68:71], v[0:15]
	ds_read_b128 v[234:237], v230 offset:96
	s_waitcnt lgkmcnt(11)
	v_mfma_f32_32x32x16_bf16 v[80:95], v[192:195], v[96:99], 0
	ds_read_b128 v[238:241], v230 offset:10848
	s_waitcnt lgkmcnt(11)
	v_mfma_f32_32x32x16_bf16 v[64:79], v[196:199], v[96:99], 0
	ds_read_b128 v[192:195], v230 offset:128
	s_waitcnt lgkmcnt(6)
	v_mfma_f32_32x32x16_bf16 v[80:95], v[200:203], v[100:103], v[80:95]
	ds_read_b128 v[196:199], v230 offset:10880
	s_waitcnt lgkmcnt(6)
	v_mfma_f32_32x32x16_bf16 v[64:79], v[204:207], v[100:103], v[64:79]
	ds_read_b128 v[200:203], v230 offset:160
	s_waitcnt lgkmcnt(6)
	v_mfma_f32_32x32x16_bf16 v[80:95], v[208:211], v[104:107], v[80:95]
	ds_read_b128 v[204:207], v230 offset:10912
	s_waitcnt lgkmcnt(6)
	v_mfma_f32_32x32x16_bf16 v[64:79], v[226:229], v[104:107], v[64:79]
	ds_read_b128 v[208:211], v230 offset:192
	s_waitcnt lgkmcnt(6)
	v_mfma_f32_32x32x16_bf16 v[80:95], v[234:237], v[108:111], v[80:95]
	ds_read_b128 v[226:229], v230 offset:10944
	s_waitcnt lgkmcnt(6)
	v_mfma_f32_32x32x16_bf16 v[64:79], v[238:241], v[108:111], v[64:79]
	ds_read_b128 v[234:237], v230 offset:224
	s_waitcnt lgkmcnt(6)
	v_mfma_f32_32x32x16_bf16 v[80:95], v[192:195], v[112:115], v[80:95]
	ds_read_b128 v[238:241], v230 offset:10976
	s_waitcnt lgkmcnt(6)
	v_mfma_f32_32x32x16_bf16 v[64:79], v[196:199], v[112:115], v[64:79]
	ds_read_b128 v[192:195], v230 offset:256
	s_waitcnt lgkmcnt(6)
	v_mfma_f32_32x32x16_bf16 v[80:95], v[200:203], v[116:119], v[80:95]
	ds_read_b128 v[196:199], v230 offset:11008
	s_waitcnt lgkmcnt(6)
	v_mfma_f32_32x32x16_bf16 v[64:79], v[204:207], v[116:119], v[64:79]
	ds_read_b128 v[200:203], v230 offset:288
	s_waitcnt lgkmcnt(6)
	v_mfma_f32_32x32x16_bf16 v[80:95], v[208:211], v[120:123], v[80:95]
	ds_read_b128 v[204:207], v230 offset:11040
	s_waitcnt lgkmcnt(6)
	v_mfma_f32_32x32x16_bf16 v[64:79], v[226:229], v[120:123], v[64:79]
	s_waitcnt lgkmcnt(5)
	v_mfma_f32_32x32x16_bf16 v[80:95], v[234:237], v[124:127], v[80:95]
	s_waitcnt lgkmcnt(4)
	v_mfma_f32_32x32x16_bf16 v[64:79], v[238:241], v[124:127], v[64:79]
	s_waitcnt lgkmcnt(3)
	v_mfma_f32_32x32x16_bf16 v[80:95], v[192:195], v[128:131], v[80:95]
	s_waitcnt lgkmcnt(2)
	v_mfma_f32_32x32x16_bf16 v[64:79], v[196:199], v[128:131], v[64:79]
	s_waitcnt lgkmcnt(1)
	v_mfma_f32_32x32x16_bf16 v[80:95], v[200:203], v[132:135], v[80:95]
	s_waitcnt lgkmcnt(0)
	v_mfma_f32_32x32x16_bf16 v[64:79], v[204:207], v[132:135], v[64:79]
	s_waitcnt lgkmcnt(0)
	s_mov_b32 s25, s22
	s_mov_b32 s22, s23
	s_mov_b32 s23, s24
	s_mov_b32 s24, s25
	s_add_i32 s20, s20, 1
	s_branch .Lattn_loop
.Lattn_xlast:
	s_waitcnt lgkmcnt(6)
	v_mfma_f32_32x32x16_bf16 v[48:63], v[192:195], v[80:83], v[48:63]
	ds_read_b128 v[238:241], v231 offset:26208
	s_waitcnt lgkmcnt(6)
	v_mfma_f32_32x32x16_bf16 v[48:63], v[196:199], v[84:87], v[48:63]
	ds_read_b128 v[192:195], v231 offset:30720
	s_waitcnt lgkmcnt(6)
	v_mfma_f32_32x32x16_bf16 v[48:63], v[200:203], v[64:67], v[48:63]
	ds_read_b128 v[196:199], v231 offset:30752
	s_waitcnt lgkmcnt(6)
	v_mfma_f32_32x32x16_bf16 v[48:63], v[204:207], v[68:71], v[48:63]
	ds_read_b128 v[200:203], v231 offset:30784
	s_waitcnt lgkmcnt(6)
	v_mfma_f32_32x32x16_bf16 v[32:47], v[208:211], v[80:83], v[32:47]
	ds_read_b128 v[204:207], v231 offset:30816
	s_waitcnt lgkmcnt(6)
	v_mfma_f32_32x32x16_bf16 v[32:47], v[226:229], v[84:87], v[32:47]
	ds_read_b128 v[208:211], v231 offset:35328
	s_waitcnt lgkmcnt(6)
	v_mfma_f32_32x32x16_bf16 v[32:47], v[234:237], v[64:67], v[32:47]
	ds_read_b128 v[226:229], v231 offset:35360
	s_waitcnt lgkmcnt(6)
	v_mfma_f32_32x32x16_bf16 v[32:47], v[238:241], v[68:71], v[32:47]
	ds_read_b128 v[234:237], v231 offset:35392
	s_waitcnt lgkmcnt(6)
	v_mfma_f32_32x32x16_bf16 v[16:31], v[192:195], v[80:83], v[16:31]
	ds_read_b128 v[238:241], v231 offset:35424
	s_waitcnt lgkmcnt(6)
	v_mfma_f32_32x32x16_bf16 v[16:31], v[196:199], v[84:87], v[16:31]
	s_waitcnt lgkmcnt(5)
	v_mfma_f32_32x32x16_bf16 v[16:31], v[200:203], v[64:67], v[16:31]
	s_waitcnt lgkmcnt(4)
	v_mfma_f32_32x32x16_bf16 v[16:31], v[204:207], v[68:71], v[16:31]
	s_waitcnt lgkmcnt(3)
	v_mfma_f32_32x32x16_bf16 v[0:15], v[208:211], v[80:83], v[0:15]
	s_waitcnt lgkmcnt(2)
	v_mfma_f32_32x32x16_bf16 v[0:15], v[226:229], v[84:87], v[0:15]
	s_waitcnt lgkmcnt(1)
	v_mfma_f32_32x32x16_bf16 v[0:15], v[234:237], v[64:67], v[0:15]
	s_waitcnt lgkmcnt(0)
	v_mfma_f32_32x32x16_bf16 v[0:15], v[238:241], v[68:71], v[0:15]
	s_waitcnt lgkmcnt(0)
	s_cmp_lt_u32 s88, 4
	s_cbranch_scc0 .Lattn_done
	s_barrier
.Lattn_done:
	s_nop 15
	s_nop 3
	v_mov_b32_e32 v64, v167
	s_branch .LBB0_688
